# rowop<4> kind 0 (phase 1): the 12 gpre/sc/sh parameter loads issued right after the row loads (address slices re-run early), recounted waits
# speedup vs baseline: 1.0035x; 1.0035x over previous
.LBB0_1023:
	s_or_b64 exec, exec, s[0:1]
	v_lshl_add_u64 v[0:1], v[0:1], 0, v[192:193]
	global_load_dwordx4 v[60:63], v[0:1], off nt
	global_load_dwordx4 v[44:47], v[0:1], off offset:1024 nt
	global_load_dwordx4 v[28:31], v[0:1], off offset:2048 nt
	global_load_dwordx4 v[12:15], v[0:1], off offset:3072 nt
	v_add_co_u32_e32 v2, vcc, 0x1000, v0
	v_min_i32_e32 v67, 0x4000, v80
	s_nop 0
	v_addc_co_u32_e32 v3, vcc, 0, v1, vcc
	global_load_dwordx4 v[56:59], v[2:3], off nt
	global_load_dwordx4 v[40:43], v[2:3], off offset:1024 nt
	global_load_dwordx4 v[24:27], v[2:3], off offset:2048 nt
	global_load_dwordx4 v[8:11], v[2:3], off offset:3072 nt
	v_add_co_u32_e32 v2, vcc, 0x2000, v0
	s_mov_b64 s[0:1], vcc
	s_nop 0
	v_addc_co_u32_e64 v3, s[0:1], 0, v1, s[0:1]
	global_load_dwordx4 v[52:55], v[2:3], off nt
	global_load_dwordx4 v[36:39], v[2:3], off offset:1024 nt
	global_load_dwordx4 v[20:23], v[2:3], off offset:2048 nt
	global_load_dwordx4 v[4:7], v[2:3], off offset:3072 nt
	v_add_co_u32_e32 v0, vcc, 0x3000, v0
	v_ashrrev_i32_e32 v67, 13, v67
	s_nop 0
	v_addc_co_u32_e32 v1, vcc, 0, v1, vcc
	global_load_dwordx4 v[48:51], v[0:1], off nt
	global_load_dwordx4 v[32:35], v[0:1], off offset:1024 nt
	global_load_dwordx4 v[16:19], v[0:1], off offset:2048 nt
	s_nop 0
	global_load_dwordx4 v[0:3], v[0:1], off offset:3072 nt
	s_mov_b64 s[0:1], 0x1000
	v_mov_b32_e32 v136, v193
	v_mov_b32_e32 v137, v193
	v_mul_hi_i32_i24_e32 v138, 0x6000, v67
	v_mul_i32_i24_e32 v139, 0x6000, v67
	v_mov_b32_e32 v140, v139
	v_mov_b32_e32 v141, v138
	v_lshl_add_u64 v[142:143], s[96:97], 0, v[140:141]
	v_lshl_add_u64 v[140:141], v[142:143], 0, s[0:1]
	v_lshl_add_u64 v[144:145], v[140:141], 0, v[192:193]
	global_load_dwordx4 v[146:149], v[144:145], off
	global_load_dwordx4 v[150:153], v[76:77], off
	v_lshl_add_u64 v[138:139], v[142:143], 0, v[192:193]
	global_load_dwordx4 v[154:157], v[138:139], off
	v_mov_b32_e32 v158, v193
	v_mov_b32_e32 v160, v82
	v_mov_b32_e32 v161, v158
	v_lshl_add_u64 v[162:163], v[140:141], 0, v[160:161]
	global_load_dwordx4 v[164:167], v[162:163], off
	global_load_dwordx4 v[172:175], v[76:77], off offset:1024
	global_load_dwordx4 v[180:183], v[138:139], off offset:1024
	v_mov_b32_e32 v160, v84
	v_mov_b32_e32 v161, v136
	v_lshl_add_u64 v[176:177], v[140:141], 0, v[160:161]
	global_load_dwordx4 v[184:187], v[176:177], off
	global_load_dwordx4 v[188:191], v[76:77], off offset:2048
	global_load_dwordx4 v[232:235], v[138:139], off offset:2048
	v_mov_b32_e32 v160, v86
	v_mov_b32_e32 v161, v137
	v_lshl_add_u64 v[224:225], v[140:141], 0, v[160:161]
	global_load_dwordx4 v[236:239], v[224:225], off
	global_load_dwordx4 v[240:243], v[76:77], off offset:3072
	global_load_dwordx4 v[248:251], v[138:139], off offset:3072
	s_mov_b64 s[0:1], 0x1000
	s_mov_b32 s6, 0x3a800000
	s_mov_b32 s2, 0x800000
	v_mov_b32_e32 v85, v193
	v_mov_b32_e32 v87, v193
	s_add_i32 s4, s4, s93
	s_cmpk_gt_i32 s4, 0x3ff
	s_waitcnt vmcnt(27)
	v_mov_b32_e32 v94, v61
	s_waitcnt vmcnt(26)
	v_mov_b32_e32 v95, v45
	s_waitcnt vmcnt(25)
	v_mov_b32_e32 v102, v29
	s_waitcnt vmcnt(24)
	v_mov_b32_e32 v103, v13
	v_mov_b32_e32 v90, v60
	v_mov_b32_e32 v91, v44
	v_mov_b32_e32 v100, v28
	v_mov_b32_e32 v101, v12
	v_pk_mul_f32 v[94:95], v[94:95], v[94:95]
	v_pk_mul_f32 v[102:103], v[102:103], v[102:103]
	v_mov_b32_e32 v96, v62
	v_mov_b32_e32 v97, v46
	v_pk_fma_f32 v[90:91], v[90:91], v[90:91], v[94:95]
	v_pk_fma_f32 v[94:95], v[100:101], v[100:101], v[102:103]
	s_waitcnt vmcnt(23)
	v_mov_b32_e32 v102, v57
	s_waitcnt vmcnt(22)
	v_mov_b32_e32 v103, v41
	v_mov_b32_e32 v100, v56
	v_mov_b32_e32 v101, v40
	s_waitcnt vmcnt(21)
	v_mov_b32_e32 v114, v25
	s_waitcnt vmcnt(20)
	v_mov_b32_e32 v115, v9
	v_pk_fma_f32 v[90:91], v[96:97], v[96:97], v[90:91]
	v_pk_mul_f32 v[96:97], v[102:103], v[102:103]
	v_mov_b32_e32 v98, v63
	v_mov_b32_e32 v99, v47
	v_mov_b32_e32 v108, v58
	v_mov_b32_e32 v109, v42
	v_mov_b32_e32 v112, v24
	v_mov_b32_e32 v113, v8
	v_pk_mul_f32 v[102:103], v[114:115], v[114:115]
	v_pk_fma_f32 v[96:97], v[100:101], v[100:101], v[96:97]
	v_mov_b32_e32 v104, v30
	v_mov_b32_e32 v105, v14
	v_mov_b32_e32 v110, v59
	v_mov_b32_e32 v111, v43
	v_mov_b32_e32 v116, v26
	v_mov_b32_e32 v117, v10
	v_pk_fma_f32 v[90:91], v[98:99], v[98:99], v[90:91]
	v_pk_fma_f32 v[98:99], v[112:113], v[112:113], v[102:103]
	v_pk_fma_f32 v[96:97], v[108:109], v[108:109], v[96:97]
	v_mov_b32_e32 v106, v31
	v_mov_b32_e32 v107, v15
	v_mov_b32_e32 v118, v27
	v_mov_b32_e32 v119, v11
	v_pk_fma_f32 v[94:95], v[104:105], v[104:105], v[94:95]
	v_pk_fma_f32 v[98:99], v[116:117], v[116:117], v[98:99]
	v_pk_fma_f32 v[96:97], v[110:111], v[110:111], v[96:97]
	v_pk_fma_f32 v[94:95], v[106:107], v[106:107], v[94:95]
	v_mov_b32_e32 v101, v90
	v_pk_fma_f32 v[98:99], v[118:119], v[118:119], v[98:99]
	v_mov_b32_e32 v100, v96
	v_mov_b32_e32 v90, v97
	v_mov_b32_e32 v103, v94
	v_mov_b32_e32 v102, v98
	v_pk_add_f32 v[90:91], v[100:101], v[90:91]
	v_mov_b32_e32 v94, v99
	v_pk_add_f32 v[90:91], v[90:91], v[102:103]
	v_add_u32_e32 v96, 1, v80
	v_pk_add_f32 v[90:91], v[90:91], v[94:95]
	ds_bpermute_b32 v95, v65, v91
	ds_bpermute_b32 v94, v65, v90
	v_ashrrev_i32_e32 v97, 31, v96
	v_mul_hi_i32_i24_e32 v105, 0x6000, v67
	v_mul_i32_i24_e32 v104, 0x6000, v67
	v_lshlrev_b64 v[102:103], 11, v[96:97]
	s_waitcnt lgkmcnt(0)
	v_pk_add_f32 v[90:91], v[90:91], v[94:95]
	ds_bpermute_b32 v95, v71, v91
	ds_bpermute_b32 v94, v71, v90
	v_lshl_add_u64 v[96:97], s[96:97], 0, v[104:105]
	s_waitcnt vmcnt(19)
	v_mov_b32_e32 v104, v52
	s_waitcnt vmcnt(18)
	v_mov_b32_e32 v105, v36
	s_waitcnt vmcnt(13)
	v_mov_b32_e32 v108, v17
	s_waitcnt lgkmcnt(0)
	v_pk_add_f32 v[90:91], v[90:91], v[94:95]
	ds_bpermute_b32 v95, v73, v91
	ds_bpermute_b32 v94, v73, v90
	s_waitcnt vmcnt(12)
	v_mov_b32_e32 v109, v1
	v_pk_mul_f32 v[108:109], v[108:109], v[108:109]
	v_mov_b32_e32 v128, v19
	v_mov_b32_e32 v129, v3
	s_waitcnt lgkmcnt(0)
	v_pk_add_f32 v[116:117], v[90:91], v[94:95]
	v_mov_b32_e32 v90, v53
	v_mov_b32_e32 v91, v37
	v_pk_mul_f32 v[90:91], v[90:91], v[90:91]
	v_mov_b32_e32 v94, v54
	v_pk_fma_f32 v[90:91], v[104:105], v[104:105], v[90:91]
	v_mov_b32_e32 v95, v38
	v_pk_fma_f32 v[90:91], v[94:95], v[94:95], v[90:91]
	v_mov_b32_e32 v94, v55
	v_mov_b32_e32 v95, v39
	v_pk_fma_f32 v[120:121], v[94:95], v[94:95], v[90:91]
	v_mov_b32_e32 v94, v21
	v_mov_b32_e32 v95, v5
	v_mov_b32_e32 v90, v20
	v_mov_b32_e32 v91, v4
	v_pk_mul_f32 v[94:95], v[94:95], v[94:95]
	ds_bpermute_b32 v119, v75, v117
	v_pk_fma_f32 v[90:91], v[90:91], v[90:91], v[94:95]
	v_mov_b32_e32 v94, v22
	v_mov_b32_e32 v95, v6
	v_pk_fma_f32 v[90:91], v[94:95], v[94:95], v[90:91]
	v_mov_b32_e32 v94, v23
	v_mov_b32_e32 v95, v7
	v_pk_fma_f32 v[122:123], v[94:95], v[94:95], v[90:91]
	v_mov_b32_e32 v94, v49
	v_mov_b32_e32 v95, v33
	v_mov_b32_e32 v90, v48
	v_mov_b32_e32 v91, v32
	v_pk_mul_f32 v[94:95], v[94:95], v[94:95]
	ds_bpermute_b32 v118, v75, v116
	v_pk_fma_f32 v[90:91], v[90:91], v[90:91], v[94:95]
	v_mov_b32_e32 v94, v50
	v_mov_b32_e32 v95, v34
	v_pk_fma_f32 v[90:91], v[94:95], v[94:95], v[90:91]
	v_mov_b32_e32 v94, v51
	v_mov_b32_e32 v95, v35
	v_pk_fma_f32 v[124:125], v[94:95], v[94:95], v[90:91]
	v_lshl_add_u64 v[90:91], v[96:97], 0, s[0:1]
	v_lshl_add_u64 v[104:105], v[90:91], 0, v[192:193]
	v_mov_b32_e32 v94, v16
	v_mov_b32_e32 v95, v0
	v_pk_fma_f32 v[94:95], v[94:95], v[94:95], v[108:109]
	v_mov_b32_e32 v108, v18
	v_mov_b32_e32 v109, v2
	v_pk_fma_f32 v[126:127], v[108:109], v[108:109], v[94:95]
	v_lshl_add_u64 v[94:95], v[96:97], 0, v[192:193]
	v_pk_fma_f32 v[96:97], v[128:129], v[128:129], v[126:127]
	v_mov_b32_e32 v126, v124
	v_mov_b32_e32 v127, v120
	v_mov_b32_e32 v120, v125
	v_pk_add_f32 v[120:121], v[126:127], v[120:121]
	v_mov_b32_e32 v124, v96
	v_mov_b32_e32 v125, v122
	v_pk_add_f32 v[120:121], v[120:121], v[124:125]
	v_mov_b32_e32 v122, v97
	v_pk_add_f32 v[96:97], v[120:121], v[122:123]
	ds_bpermute_b32 v121, v65, v97
	ds_bpermute_b32 v120, v65, v96
	v_add_u32_e32 v100, 2, v80
	v_ashrrev_i32_e32 v101, 31, v100
	v_lshlrev_b64 v[122:123], 11, v[100:101]
	s_waitcnt lgkmcnt(2)
	v_pk_add_f32 v[100:101], v[116:117], v[118:119]
	s_waitcnt lgkmcnt(0)
	v_pk_add_f32 v[96:97], v[96:97], v[120:121]
	ds_bpermute_b32 v119, v71, v97
	ds_bpermute_b32 v118, v71, v96
	ds_bpermute_b32 v117, v89, v101
	ds_bpermute_b32 v116, v89, v100
	s_mov_b32 s0, 0x358637bd
	v_lshlrev_b64 v[98:99], 11, v[80:81]
	s_waitcnt lgkmcnt(2)
	v_pk_add_f32 v[96:97], v[96:97], v[118:119]
	ds_bpermute_b32 v119, v73, v97
	ds_bpermute_b32 v118, v73, v96
	s_waitcnt lgkmcnt(2)
	v_pk_add_f32 v[100:101], v[100:101], v[116:117]
	ds_bpermute_b32 v117, v93, v101
	ds_bpermute_b32 v116, v93, v100
	v_add_u32_e32 v120, 3, v80
	s_waitcnt lgkmcnt(2)
	v_pk_add_f32 v[96:97], v[96:97], v[118:119]
	ds_bpermute_b32 v119, v75, v97
	ds_bpermute_b32 v118, v75, v96
	s_waitcnt lgkmcnt(2)
	v_pk_add_f32 v[100:101], v[100:101], v[116:117]
	v_mov_b64_e32 v[116:117], s[0:1]
	v_pk_fma_f32 v[100:101], v[100:101], s[6:7], v[116:117] op_sel_hi:[1,0,0]
	v_lshl_add_u64 v[98:99], v[78:79], 0, v[98:99]
	s_waitcnt lgkmcnt(0)
	v_pk_add_f32 v[96:97], v[96:97], v[118:119]
	ds_bpermute_b32 v119, v89, v97
	ds_bpermute_b32 v118, v89, v96
	v_mul_f32_e32 v67, 0x4b800000, v101
	v_cmp_gt_f32_e32 vcc, s2, v101
	v_mul_f32_e32 v69, 0x4b800000, v100
	v_cmp_gt_f32_e64 s[0:1], s2, v100
	s_waitcnt lgkmcnt(0)
	v_pk_add_f32 v[96:97], v[96:97], v[118:119]
	ds_bpermute_b32 v119, v93, v97
	ds_bpermute_b32 v118, v93, v96
	v_cndmask_b32_e32 v67, v101, v67, vcc
	v_rsq_f32_e32 v67, v67
	v_cndmask_b32_e64 v69, v100, v69, s[0:1]
	v_rsq_f32_e32 v69, v69
	s_waitcnt lgkmcnt(0)
	v_pk_add_f32 v[96:97], v[96:97], v[118:119]
	v_mul_f32_e32 v81, 0x45800000, v67
	v_pk_fma_f32 v[96:97], v[96:97], s[6:7], v[116:117] op_sel_hi:[1,0,0]
	v_cndmask_b32_e32 v100, v67, v81, vcc
	v_mul_f32_e32 v81, 0x4b800000, v97
	v_cmp_gt_f32_e32 vcc, s2, v97
	v_mul_f32_e32 v83, 0x4b800000, v96
	v_cmp_gt_f32_e64 s[2:3], s2, v96
	v_cndmask_b32_e32 v81, v97, v81, vcc
	v_rsq_f32_e32 v81, v81
	v_cndmask_b32_e64 v83, v96, v83, s[2:3]
	v_rsq_f32_e32 v83, v83
	v_mul_f32_e32 v67, 0x45800000, v69
	v_cndmask_b32_e64 v96, v69, v67, s[0:1]
	v_mul_f32_e32 v67, 0x45800000, v81
	v_cndmask_b32_e32 v92, v81, v67, vcc
	v_mul_f32_e32 v67, 0x45800000, v83
	v_cndmask_b32_e64 v88, v83, v67, s[2:3]
	v_ashrrev_i32_e32 v121, 31, v120
	v_lshlrev_b64 v[120:121], 11, v[120:121]
	v_mov_b32_e32 v83, v193
	s_waitcnt vmcnt(11)
	v_mov_b32_e32 v104, v146
	v_mov_b32_e32 v105, v147
	v_mov_b32_e32 v106, v148
	v_mov_b32_e32 v107, v149
	v_mov_b32_e32 v117, v106
	v_mov_b32_e32 v106, v105
	v_mov_b32_e32 v116, v104
	v_pk_add_f32 v[104:105], v[106:107], 1.0 op_sel_hi:[1,0]
	v_mov_b32_e32 v107, v62
	v_mov_b32_e32 v62, v61
	v_mov_b32_e32 v106, v60
	s_waitcnt vmcnt(10)
	v_mov_b32_e32 v108, v150
	v_mov_b32_e32 v109, v151
	v_mov_b32_e32 v110, v152
	v_mov_b32_e32 v111, v153
	v_mov_b32_e32 v119, v110
	v_pk_mul_f32 v[60:61], v[62:63], v[100:101] op_sel_hi:[1,0]
	v_mov_b32_e32 v110, v109
	v_pk_mul_f32 v[106:107], v[106:107], v[100:101] op_sel_hi:[1,0]
	v_mov_b32_e32 v118, v108
	s_waitcnt vmcnt(9)
	v_mov_b32_e32 v112, v154
	v_mov_b32_e32 v113, v155
	v_mov_b32_e32 v114, v156
	v_mov_b32_e32 v115, v157
	v_mov_b32_e32 v125, v114
	v_pk_mul_f32 v[60:61], v[60:61], v[110:111]
	v_mov_b32_e32 v114, v113
	v_pk_add_f32 v[116:117], v[116:117], 1.0 op_sel_hi:[1,0]
	v_pk_mul_f32 v[106:107], v[106:107], v[118:119]
	v_mov_b32_e32 v124, v112
	v_pk_fma_f32 v[60:61], v[60:61], v[104:105], v[114:115]
	v_pk_fma_f32 v[106:107], v[106:107], v[116:117], v[124:125]
	v_cvt_pk_bf16_f32 v61, v107, v61
	v_cvt_pk_bf16_f32 v60, v106, v60
	v_mov_b32_e32 v62, v56
	v_mov_b32_e32 v63, v58
	v_pk_mul_f32 v[62:63], v[62:63], v[96:97] op_sel_hi:[1,0]
	v_mov_b32_e32 v58, v57
	v_pk_mul_f32 v[62:63], v[62:63], v[118:119]
	v_pk_mul_f32 v[56:57], v[58:59], v[96:97] op_sel_hi:[1,0]
	v_pk_fma_f32 v[62:63], v[62:63], v[116:117], v[124:125]
	v_pk_mul_f32 v[56:57], v[56:57], v[110:111]
	v_pk_fma_f32 v[56:57], v[56:57], v[104:105], v[114:115]
	v_cvt_pk_bf16_f32 v56, v62, v56
	v_cvt_pk_bf16_f32 v57, v63, v57
	v_mov_b32_e32 v58, v52
	v_mov_b32_e32 v59, v54
	v_pk_mul_f32 v[58:59], v[58:59], v[92:93] op_sel_hi:[1,0]
	v_mov_b32_e32 v54, v53
	v_pk_mul_f32 v[58:59], v[118:119], v[58:59]
	v_pk_mul_f32 v[52:53], v[54:55], v[92:93] op_sel_hi:[1,0]
	v_pk_fma_f32 v[58:59], v[58:59], v[116:117], v[124:125]
	v_pk_mul_f32 v[52:53], v[110:111], v[52:53]
	v_pk_fma_f32 v[52:53], v[52:53], v[104:105], v[114:115]
	v_cvt_pk_bf16_f32 v52, v58, v52
	v_cvt_pk_bf16_f32 v53, v59, v53
	v_mov_b32_e32 v54, v48
	v_mov_b32_e32 v55, v50
	v_pk_mul_f32 v[54:55], v[54:55], v[88:89] op_sel_hi:[1,0]
	v_mov_b32_e32 v50, v49
	v_pk_mul_f32 v[54:55], v[118:119], v[54:55]
	v_pk_mul_f32 v[48:49], v[50:51], v[88:89] op_sel_hi:[1,0]
	v_pk_fma_f32 v[54:55], v[116:117], v[54:55], v[124:125]
	v_pk_mul_f32 v[48:49], v[110:111], v[48:49]
	v_pk_fma_f32 v[48:49], v[104:105], v[48:49], v[114:115]
	v_cvt_pk_bf16_f32 v48, v54, v48
	v_cvt_pk_bf16_f32 v49, v55, v49
	global_store_dwordx2 v[98:99], v[60:61], off nt
	v_lshl_add_u64 v[60:61], v[78:79], 0, v[102:103]
	global_store_dwordx2 v[60:61], v[56:57], off nt
	v_lshl_add_u64 v[56:57], v[78:79], 0, v[122:123]
	global_store_dwordx2 v[56:57], v[52:53], off nt
	v_lshl_add_u64 v[52:53], v[78:79], 0, v[120:121]
	global_store_dwordx2 v[52:53], v[48:49], off nt
	v_lshl_add_u64 v[48:49], v[90:91], 0, v[82:83]
	s_nop 0
	v_readlane_b32 s0, v255, 7
	s_waitcnt vmcnt(12)
	v_mov_b32_e32 v48, v164
	v_mov_b32_e32 v49, v165
	v_mov_b32_e32 v50, v166
	v_mov_b32_e32 v51, v167
	v_mov_b32_e32 v55, v50
	v_mov_b32_e32 v50, v49
	v_mov_b32_e32 v54, v48
	v_pk_add_f32 v[48:49], v[50:51], 1.0 op_sel_hi:[1,0]
	v_mov_b32_e32 v50, v44
	v_mov_b32_e32 v51, v46
	v_pk_mul_f32 v[50:51], v[50:51], v[100:101] op_sel_hi:[1,0]
	s_waitcnt vmcnt(11)
	v_mov_b32_e32 v102, v172
	v_mov_b32_e32 v103, v173
	v_mov_b32_e32 v104, v174
	v_mov_b32_e32 v105, v175
	v_mov_b32_e32 v58, v102
	v_mov_b32_e32 v59, v104
	v_mov_b32_e32 v46, v45
	v_pk_add_f32 v[54:55], v[54:55], 1.0 op_sel_hi:[1,0]
	v_pk_mul_f32 v[50:51], v[50:51], v[58:59]
	s_waitcnt vmcnt(10)
	v_mov_b32_e32 v106, v180
	v_mov_b32_e32 v107, v181
	v_mov_b32_e32 v108, v182
	v_mov_b32_e32 v109, v183
	v_mov_b32_e32 v62, v106
	v_mov_b32_e32 v63, v108
	v_pk_mul_f32 v[44:45], v[46:47], v[100:101] op_sel_hi:[1,0]
	v_mov_b32_e32 v104, v103
	v_pk_fma_f32 v[50:51], v[50:51], v[54:55], v[62:63]
	v_pk_mul_f32 v[44:45], v[44:45], v[104:105]
	v_mov_b32_e32 v108, v107
	v_pk_fma_f32 v[44:45], v[44:45], v[48:49], v[108:109]
	v_cvt_pk_bf16_f32 v44, v50, v44
	v_cvt_pk_bf16_f32 v45, v51, v45
	global_store_dwordx2 v[98:99], v[44:45], off offset:512 nt
	v_mov_b32_e32 v44, v40
	v_mov_b32_e32 v45, v42
	v_pk_mul_f32 v[44:45], v[44:45], v[96:97] op_sel_hi:[1,0]
	v_mov_b32_e32 v42, v41
	v_pk_mul_f32 v[44:45], v[44:45], v[58:59]
	v_pk_mul_f32 v[40:41], v[42:43], v[96:97] op_sel_hi:[1,0]
	v_pk_fma_f32 v[44:45], v[44:45], v[54:55], v[62:63]
	v_pk_mul_f32 v[40:41], v[40:41], v[104:105]
	v_pk_fma_f32 v[40:41], v[40:41], v[48:49], v[108:109]
	v_cvt_pk_bf16_f32 v40, v44, v40
	v_cvt_pk_bf16_f32 v41, v45, v41
	global_store_dwordx2 v[60:61], v[40:41], off offset:512 nt
	v_mov_b32_e32 v40, v36
	v_mov_b32_e32 v41, v38
	v_pk_mul_f32 v[40:41], v[40:41], v[92:93] op_sel_hi:[1,0]
	v_mov_b32_e32 v38, v37
	v_pk_mul_f32 v[40:41], v[40:41], v[58:59]
	v_pk_mul_f32 v[36:37], v[38:39], v[92:93] op_sel_hi:[1,0]
	v_pk_fma_f32 v[40:41], v[40:41], v[54:55], v[62:63]
	v_pk_mul_f32 v[36:37], v[36:37], v[104:105]
	v_pk_fma_f32 v[36:37], v[36:37], v[48:49], v[108:109]
	v_cvt_pk_bf16_f32 v36, v40, v36
	v_cvt_pk_bf16_f32 v37, v41, v37
	global_store_dwordx2 v[56:57], v[36:37], off offset:512 nt
	v_mov_b32_e32 v36, v32
	v_mov_b32_e32 v37, v34
	v_pk_mul_f32 v[36:37], v[36:37], v[88:89] op_sel_hi:[1,0]
	v_mov_b32_e32 v34, v33
	v_pk_mul_f32 v[36:37], v[36:37], v[58:59]
	v_pk_mul_f32 v[32:33], v[34:35], v[88:89] op_sel_hi:[1,0]
	v_pk_fma_f32 v[36:37], v[36:37], v[54:55], v[62:63]
	v_pk_mul_f32 v[32:33], v[32:33], v[104:105]
	v_pk_fma_f32 v[32:33], v[32:33], v[48:49], v[108:109]
	v_cvt_pk_bf16_f32 v32, v36, v32
	v_cvt_pk_bf16_f32 v33, v37, v33
	global_store_dwordx2 v[52:53], v[32:33], off offset:512 nt
	v_lshl_add_u64 v[32:33], v[90:91], 0, v[84:85]
	s_nop 0
	v_add_u32_e32 v80, s0, v80
	s_waitcnt vmcnt(13)
	v_mov_b32_e32 v32, v184
	v_mov_b32_e32 v33, v185
	v_mov_b32_e32 v34, v186
	v_mov_b32_e32 v35, v187
	v_mov_b32_e32 v45, v34
	v_mov_b32_e32 v34, v33
	v_mov_b32_e32 v44, v32
	v_pk_add_f32 v[32:33], v[34:35], 1.0 op_sel_hi:[1,0]
	v_mov_b32_e32 v34, v28
	v_mov_b32_e32 v35, v30
	v_pk_mul_f32 v[34:35], v[34:35], v[100:101] op_sel_hi:[1,0]
	s_waitcnt vmcnt(12)
	v_mov_b32_e32 v36, v188
	v_mov_b32_e32 v37, v189
	v_mov_b32_e32 v38, v190
	v_mov_b32_e32 v39, v191
	v_mov_b32_e32 v46, v36
	v_mov_b32_e32 v47, v38
	v_mov_b32_e32 v30, v29
	v_pk_add_f32 v[44:45], v[44:45], 1.0 op_sel_hi:[1,0]
	v_pk_mul_f32 v[34:35], v[34:35], v[46:47]
	s_waitcnt vmcnt(11)
	v_mov_b32_e32 v40, v232
	v_mov_b32_e32 v41, v233
	v_mov_b32_e32 v42, v234
	v_mov_b32_e32 v43, v235
	v_mov_b32_e32 v48, v40
	v_mov_b32_e32 v49, v42
	v_pk_mul_f32 v[28:29], v[30:31], v[100:101] op_sel_hi:[1,0]
	v_mov_b32_e32 v38, v37
	v_pk_fma_f32 v[34:35], v[34:35], v[44:45], v[48:49]
	v_pk_mul_f32 v[28:29], v[28:29], v[38:39]
	v_mov_b32_e32 v42, v41
	v_pk_fma_f32 v[28:29], v[28:29], v[32:33], v[42:43]
	v_cvt_pk_bf16_f32 v28, v34, v28
	v_cvt_pk_bf16_f32 v29, v35, v29
	global_store_dwordx2 v[98:99], v[28:29], off offset:1024 nt
	v_mov_b32_e32 v28, v24
	v_mov_b32_e32 v29, v26
	v_pk_mul_f32 v[28:29], v[28:29], v[96:97] op_sel_hi:[1,0]
	v_mov_b32_e32 v26, v25
	v_pk_mul_f32 v[28:29], v[28:29], v[46:47]
	v_pk_mul_f32 v[24:25], v[26:27], v[96:97] op_sel_hi:[1,0]
	v_pk_fma_f32 v[28:29], v[28:29], v[44:45], v[48:49]
	v_pk_mul_f32 v[24:25], v[24:25], v[38:39]
	v_pk_fma_f32 v[24:25], v[24:25], v[32:33], v[42:43]
	v_cvt_pk_bf16_f32 v24, v28, v24
	v_cvt_pk_bf16_f32 v25, v29, v25
	global_store_dwordx2 v[60:61], v[24:25], off offset:1024 nt
	v_mov_b32_e32 v24, v20
	v_mov_b32_e32 v25, v22
	v_pk_mul_f32 v[24:25], v[24:25], v[92:93] op_sel_hi:[1,0]
	v_mov_b32_e32 v22, v21
	v_pk_mul_f32 v[24:25], v[24:25], v[46:47]
	v_pk_mul_f32 v[20:21], v[22:23], v[92:93] op_sel_hi:[1,0]
	v_pk_fma_f32 v[24:25], v[24:25], v[44:45], v[48:49]
	v_pk_mul_f32 v[20:21], v[20:21], v[38:39]
	v_pk_fma_f32 v[20:21], v[20:21], v[32:33], v[42:43]
	v_cvt_pk_bf16_f32 v20, v24, v20
	v_cvt_pk_bf16_f32 v21, v25, v21
	global_store_dwordx2 v[56:57], v[20:21], off offset:1024 nt
	v_mov_b32_e32 v20, v16
	v_mov_b32_e32 v21, v18
	v_pk_mul_f32 v[20:21], v[20:21], v[88:89] op_sel_hi:[1,0]
	v_mov_b32_e32 v18, v17
	v_pk_mul_f32 v[20:21], v[20:21], v[46:47]
	v_pk_mul_f32 v[16:17], v[18:19], v[88:89] op_sel_hi:[1,0]
	v_pk_fma_f32 v[20:21], v[20:21], v[44:45], v[48:49]
	v_pk_mul_f32 v[16:17], v[16:17], v[38:39]
	v_pk_fma_f32 v[16:17], v[16:17], v[32:33], v[42:43]
	v_cvt_pk_bf16_f32 v16, v20, v16
	v_cvt_pk_bf16_f32 v17, v21, v17
	global_store_dwordx2 v[52:53], v[16:17], off offset:1024 nt
	v_lshl_add_u64 v[16:17], v[90:91], 0, v[86:87]
	s_nop 0
	s_waitcnt vmcnt(14)
	v_mov_b32_e32 v16, v236
	v_mov_b32_e32 v17, v237
	v_mov_b32_e32 v18, v238
	v_mov_b32_e32 v19, v239
	v_mov_b32_e32 v29, v18
	v_mov_b32_e32 v18, v17
	v_mov_b32_e32 v28, v16
	v_pk_add_f32 v[16:17], v[18:19], 1.0 op_sel_hi:[1,0]
	v_mov_b32_e32 v18, v12
	v_mov_b32_e32 v19, v14
	v_pk_mul_f32 v[18:19], v[18:19], v[100:101] op_sel_hi:[1,0]
	s_waitcnt vmcnt(13)
	v_mov_b32_e32 v20, v240
	v_mov_b32_e32 v21, v241
	v_mov_b32_e32 v22, v242
	v_mov_b32_e32 v23, v243
	v_mov_b32_e32 v30, v20
	v_mov_b32_e32 v31, v22
	v_mov_b32_e32 v14, v13
	v_pk_add_f32 v[28:29], v[28:29], 1.0 op_sel_hi:[1,0]
	v_pk_mul_f32 v[18:19], v[18:19], v[30:31]
	s_waitcnt vmcnt(12)
	v_mov_b32_e32 v24, v248
	v_mov_b32_e32 v25, v249
	v_mov_b32_e32 v26, v250
	v_mov_b32_e32 v27, v251
	v_mov_b32_e32 v32, v24
	v_mov_b32_e32 v33, v26
	v_pk_mul_f32 v[12:13], v[14:15], v[100:101] op_sel_hi:[1,0]
	v_mov_b32_e32 v22, v21
	v_pk_fma_f32 v[18:19], v[18:19], v[28:29], v[32:33]
	v_pk_mul_f32 v[12:13], v[12:13], v[22:23]
	v_mov_b32_e32 v26, v25
	v_pk_fma_f32 v[12:13], v[12:13], v[16:17], v[26:27]
	v_cvt_pk_bf16_f32 v12, v18, v12
	v_cvt_pk_bf16_f32 v13, v19, v13
	global_store_dwordx2 v[98:99], v[12:13], off offset:1536 nt
	v_mov_b32_e32 v12, v8
	v_mov_b32_e32 v13, v10
	v_pk_mul_f32 v[12:13], v[12:13], v[96:97] op_sel_hi:[1,0]
	v_mov_b32_e32 v10, v9
	v_pk_mul_f32 v[12:13], v[12:13], v[30:31]
	v_pk_mul_f32 v[8:9], v[10:11], v[96:97] op_sel_hi:[1,0]
	v_pk_fma_f32 v[12:13], v[12:13], v[28:29], v[32:33]
	v_pk_mul_f32 v[8:9], v[8:9], v[22:23]
	v_pk_fma_f32 v[8:9], v[8:9], v[16:17], v[26:27]
	v_cvt_pk_bf16_f32 v8, v12, v8
	v_cvt_pk_bf16_f32 v9, v13, v9
	global_store_dwordx2 v[60:61], v[8:9], off offset:1536 nt
	v_mov_b32_e32 v8, v4
	v_mov_b32_e32 v9, v6
	v_pk_mul_f32 v[8:9], v[8:9], v[92:93] op_sel_hi:[1,0]
	v_mov_b32_e32 v6, v5
	v_pk_mul_f32 v[8:9], v[8:9], v[30:31]
	v_pk_mul_f32 v[4:5], v[6:7], v[92:93] op_sel_hi:[1,0]
	v_pk_fma_f32 v[8:9], v[8:9], v[28:29], v[32:33]
	v_pk_mul_f32 v[4:5], v[4:5], v[22:23]
	v_pk_fma_f32 v[4:5], v[4:5], v[16:17], v[26:27]
	v_cvt_pk_bf16_f32 v4, v8, v4
	v_cvt_pk_bf16_f32 v5, v9, v5
	global_store_dwordx2 v[56:57], v[4:5], off offset:1536 nt
	v_mov_b32_e32 v4, v0
	v_mov_b32_e32 v5, v2
	v_pk_mul_f32 v[4:5], v[4:5], v[88:89] op_sel_hi:[1,0]
	v_mov_b32_e32 v2, v1
	v_pk_mul_f32 v[4:5], v[4:5], v[30:31]
	v_pk_mul_f32 v[0:1], v[2:3], v[88:89] op_sel_hi:[1,0]
	v_pk_fma_f32 v[4:5], v[4:5], v[28:29], v[32:33]
	v_pk_mul_f32 v[0:1], v[0:1], v[22:23]
	v_pk_fma_f32 v[0:1], v[0:1], v[16:17], v[26:27]
	v_cvt_pk_bf16_f32 v0, v4, v0
	v_cvt_pk_bf16_f32 v1, v5, v1
	global_store_dwordx2 v[52:53], v[0:1], off offset:1536 nt
	s_cbranch_scc1 .LBB0_1028
